# speedup vs baseline: 1.0065x; 1.0065x over previous
; __device__ void den_phase(const Ctx& p, const int hd) {
;     ...
;     if (lane == 0) {
;       float den = s;
;       if (c > 0) den += __expf(gA[bh * SEQ + c * 2048 - 1] - gA[bh * SEQ + t]) * qn;
;       rden[row] = 1.f / fmaxf(fabsf(den), gE[bh * SEQ + t]);
;     }
.LBB0_478:
	s_andn2_saveexec_b64 s[12:13], s[12:13]
	s_or_b64 exec, exec, s[12:13]
	v_lshl_add_u64 v[2:3], v[2:3], 2, s[8:9]
	v_mov_b32_e32 v2, v104
	v_max_f32_e64 v3, |v4|, |v4|
	s_waitcnt vmcnt(0) lgkmcnt(0)
	v_max_f32_e32 v2, v2, v2
	v_max_f32_e32 v2, v3, v2
	v_div_scale_f32 v3, s[12:13], v2, v2, 1.0
	v_rcp_f32_e32 v4, v3
	v_div_scale_f32 v5, vcc, 1.0, v2, 1.0
	v_fma_f32 v6, -v3, v4, 1.0
	v_fmac_f32_e32 v4, v6, v4
	v_mul_f32_e32 v6, v5, v4
	v_fma_f32 v7, -v3, v6, v5
	v_fmac_f32_e32 v6, v7, v4
	v_fma_f32 v3, -v3, v6, v5
	v_div_fmas_f32 v3, v3, v4, v6
	v_div_fixup_f32 v4, v3, v2, 1.0
	v_lshl_add_u64 v[2:3], v[52:53], 2, s[10:11]
	global_store_dword v[2:3], v4, off

; __device__ void den_phase(const Ctx& p, const int hd) {
;     ...
;   for (int item = blockIdx.x; item < NTOK / 8; item += gridDim.x) {
;     const int row = item * 8 + w;
;     const int b = row >> 13, t = row & 8191, c = t >> 11, i = t & 2047;
;     const int bh = b * 4 + hd;
;     const int ncol = ((i >> 8) + 1) * 256;
;     const u16* pr = Ph + (((long)b * 4 + c) * 2048 + i) * 2048;
;     uint4 pv[4], qv[4];
; #pragma unroll
;     for (int k = 0; k < 4; ++k) pv[k] = *(const uint4*)(pr + k * 512 + lane * 8);
;     const u16* qr = Qh + (long)row * LDQ;
;     const float* n = nv + (b * 3 + (c > 0 ? c - 1 : 0)) * 2048;
;     float4 n0[4], n1[4];
; #pragma unroll
;     for (int k = 0; k < 4; ++k) {
;       qv[k] = *(const uint4*)(qr + k * 512 + lane * 8);
;       n0[k] = *(const float4*)(n + k * 512 + lane * 8); n1[k] = *(const float4*)(n + k * 512 + lane * 8 + 4);
;     }
;     ...
;       if (c > 0) den += __expf(gA[bh * SEQ + c * 2048 - 1] - gA[bh * SEQ + t]) * qn;
.LBB0_480:
	v_ashrrev_i32_e32 v54, 13, v52
	v_ashrrev_i32_e32 v55, 31, v54
	s_waitcnt lgkmcnt(0)
	v_and_b32_e32 v6, 0x7ff, v52
	v_lshlrev_b64 v[4:5], 13, v[54:55]
	v_and_b32_e32 v55, 0x1800, v52
	v_or3_b32 v4, v4, v55, v6
	v_mad_i64_i32 v[2:3], s[0:1], v52, s0, v[46:47]
	v_lshlrev_b64 v[4:5], 12, v[4:5]
	v_and_b32_e32 v65, 0x1fff, v52
	v_lshl_add_u32 v100, v54, 15, s20
	v_or_b32_e32 v106, v100, v65
	v_or_b32_e32 v108, v100, v55
	v_mov_b32_e32 v107, 0
	v_mov_b32_e32 v109, 0
	v_lshl_add_u64 v[110:111], v[108:109], 2, s[6:7]
	global_load_dword v102, v[110:111], off offset:-4
	v_lshl_add_u64 v[112:113], v[106:107], 2, s[6:7]
	global_load_dword v103, v[112:113], off
	v_lshl_add_u64 v[114:115], v[106:107], 2, s[8:9]
	global_load_dword v104, v[114:115], off
	v_lshl_add_u64 v[6:7], v[48:49], 0, v[4:5]
	v_bfe_u32 v4, v52, 11, 2
	s_movk_i32 s0, 0x800
	v_add_u32_e32 v4, -1, v4
	v_cmp_gt_u32_e32 vcc, s0, v65
	v_mul_i32_i24_e32 v5, 3, v54
	global_load_dwordx4 v[66:69], v[2:3], off
	v_cndmask_b32_e64 v4, v4, 0, vcc
	v_add_lshl_u32 v4, v4, v5, 11
	global_load_dwordx4 v[26:29], v[2:3], off offset:1024
	global_load_dwordx4 v[70:73], v[6:7], off
	v_ashrrev_i32_e32 v5, 31, v4
	v_lshl_add_u64 v[8:9], v[4:5], 2, v[50:51]
	global_load_dwordx4 v[74:77], v[8:9], off
	global_load_dwordx4 v[78:81], v[6:7], off offset:1024
	global_load_dwordx4 v[42:45], v[8:9], off offset:2048
	global_load_dwordx4 v[82:85], v[8:9], off offset:16
	global_load_dwordx4 v[38:41], v[8:9], off offset:2064
	global_load_dwordx4 v[18:21], v[2:3], off offset:2048
	s_nop 0
	global_load_dwordx4 v[2:5], v[2:3], off offset:3072
	s_nop 0
	global_load_dwordx4 v[34:37], v[6:7], off offset:2048
	global_load_dwordx4 v[14:17], v[6:7], off offset:3072
	v_add_co_u32_e64 v6, s[0:1], s86, v8
	v_and_b32_e32 v10, 0x700, v52
	s_nop 0
	v_addc_co_u32_e64 v7, s[0:1], 0, v9, s[0:1]
	v_add_u32_e32 v53, 0x100, v10
	global_load_dwordx4 v[30:33], v[6:7], off
	global_load_dwordx4 v[22:25], v[6:7], off offset:16
	global_load_dwordx4 v[10:13], v[6:7], off offset:2048
	s_nop 0
	global_load_dwordx4 v[6:9], v[6:7], off offset:2064
	v_cmp_lt_u32_e64 s[0:1], v62, v53
	s_waitcnt vmcnt(0) lgkmcnt(0)
; __device__ __forceinline__ float bf2f(u16 h) { return __uint_as_float(((unsigned)h) << 16); }
; __device__ void den_phase(const Ctx& p, const int hd) {
;     ...
;     float s = 0.f, qn = 0.f;
; #pragma unroll
;     for (int k = 0; k < 4; ++k) {
;       const uint4 r = pv[k];
;       const float ps = bf2f(r.x & 0xffff) + bf2f(r.x >> 16) + bf2f(r.y & 0xffff) + bf2f(r.y >> 16) +
;                        bf2f(r.z & 0xffff) + bf2f(r.z >> 16) + bf2f(r.w & 0xffff) + bf2f(r.w >> 16);
;       s += (k * 512 + lane * 8 < ncol) ? ps : 0.f;
;       const uint4 q = qv[k];
;       qn += bf2f(q.x & 0xffff) * n0[k].x + bf2f(q.x >> 16) * n0[k].y + bf2f(q.y & 0xffff) * n0[k].z + bf2f(q.y >> 16) * n0[k].w +
;             bf2f(q.z & 0xffff) * n1[k].x + bf2f(q.z >> 16) * n1[k].y + bf2f(q.w & 0xffff) * n1[k].z + bf2f(q.w >> 16) * n1[k].w;
;     }
;     if (c == 0) qn = 0.f;
;     s = wave_sum(s); qn = wave_sum(qn);
;     if (lane == 0) {
;       float den = s;
;       if (c > 0) den += __expf(gA[bh * SEQ + c * 2048 - 1] - gA[bh * SEQ + t]) * qn;
	v_lshlrev_b32_e32 v86, 16, v66
	v_and_b32_e32 v66, 0xffff0000, v66
	v_lshlrev_b32_e32 v90, 16, v26
	v_and_b32_e32 v26, 0xffff0000, v26
	v_mul_f32_e32 v26, v43, v26
	v_fmac_f32_e32 v26, v42, v90
	v_lshlrev_b32_e32 v42, 16, v27
	v_fmac_f32_e32 v26, v44, v42
	v_and_b32_e32 v27, 0xffff0000, v27
	v_fmac_f32_e32 v26, v45, v27
	v_lshlrev_b32_e32 v27, 16, v28
	v_fmac_f32_e32 v26, v38, v27
	v_and_b32_e32 v27, 0xffff0000, v28
	v_fmac_f32_e32 v26, v39, v27
	v_lshlrev_b32_e32 v27, 16, v29
	v_fmac_f32_e32 v26, v40, v27
	v_and_b32_e32 v27, 0xffff0000, v29
	v_fmac_f32_e32 v26, v41, v27
	v_lshlrev_b32_e32 v27, 16, v34
	v_and_b32_e32 v28, 0xffff0000, v34
	v_add_f32_e32 v27, v27, v28
	v_lshlrev_b32_e32 v28, 16, v35
	v_add_f32_e32 v27, v27, v28
	v_and_b32_e32 v28, 0xffff0000, v35
	v_add_f32_e32 v27, v27, v28
	v_lshlrev_b32_e32 v28, 16, v36
	v_add_f32_e32 v27, v27, v28
	v_and_b32_e32 v28, 0xffff0000, v36
	v_add_f32_e32 v27, v27, v28
	v_lshlrev_b32_e32 v28, 16, v37
	v_add_f32_e32 v27, v27, v28
	v_and_b32_e32 v28, 0xffff0000, v37
	v_add_f32_e32 v27, v27, v28
	v_lshlrev_b32_e32 v28, 16, v18
	v_and_b32_e32 v18, 0xffff0000, v18
	v_mul_f32_e32 v18, v31, v18
	v_fmac_f32_e32 v18, v30, v28
	v_lshlrev_b32_e32 v28, 16, v19
	v_fmac_f32_e32 v18, v32, v28
	v_and_b32_e32 v19, 0xffff0000, v19
	v_fmac_f32_e32 v18, v33, v19
	v_lshlrev_b32_e32 v19, 16, v20
	v_fmac_f32_e32 v18, v22, v19
	v_and_b32_e32 v19, 0xffff0000, v20
	v_fmac_f32_e32 v18, v23, v19
	v_lshlrev_b32_e32 v19, 16, v21
	v_fmac_f32_e32 v18, v24, v19
	v_and_b32_e32 v19, 0xffff0000, v21
	v_fmac_f32_e32 v18, v25, v19
	v_lshlrev_b32_e32 v19, 16, v14
	v_and_b32_e32 v14, 0xffff0000, v14
	v_add_f32_e32 v14, v19, v14
	v_lshlrev_b32_e32 v19, 16, v15
	v_add_f32_e32 v14, v14, v19
	v_and_b32_e32 v15, 0xffff0000, v15
	v_add_f32_e32 v14, v14, v15
	v_lshlrev_b32_e32 v15, 16, v16
	v_add_f32_e32 v14, v14, v15
	v_and_b32_e32 v15, 0xffff0000, v16
	v_lshlrev_b32_e32 v91, 16, v70
	v_and_b32_e32 v70, 0xffff0000, v70
	v_mul_f32_e32 v66, v75, v66
	v_lshlrev_b32_e32 v75, 16, v78
	v_and_b32_e32 v78, 0xffff0000, v78
	v_add_f32_e32 v14, v14, v15
	v_lshlrev_b32_e32 v15, 16, v17
	v_lshlrev_b32_e32 v87, 16, v67
	v_lshlrev_b32_e32 v92, 16, v71
	v_lshlrev_b32_e32 v95, 16, v79
	v_add_f32_e32 v43, v91, v70
	v_fmac_f32_e32 v66, v74, v86
	v_add_f32_e32 v70, v75, v78
	v_add_f32_e32 v14, v14, v15
	v_and_b32_e32 v15, 0xffff0000, v17
	v_and_b32_e32 v67, 0xffff0000, v67
	v_and_b32_e32 v71, 0xffff0000, v71
	v_and_b32_e32 v79, 0xffff0000, v79
	v_add_f32_e32 v43, v43, v92
	v_fmac_f32_e32 v66, v76, v87
	v_add_f32_e32 v70, v70, v95
	v_add_f32_e32 v14, v14, v15
	v_lshlrev_b32_e32 v15, 16, v2
	v_and_b32_e32 v2, 0xffff0000, v2
	v_lshlrev_b32_e32 v88, 16, v68
	v_lshlrev_b32_e32 v93, 16, v72
	v_lshlrev_b32_e32 v96, 16, v80
	v_add_f32_e32 v43, v43, v71
	v_fmac_f32_e32 v66, v77, v67
	v_add_f32_e32 v67, v70, v79
	v_mul_f32_e32 v2, v11, v2
	v_and_b32_e32 v68, 0xffff0000, v68
	v_and_b32_e32 v72, 0xffff0000, v72
	v_and_b32_e32 v80, 0xffff0000, v80
	v_add_f32_e32 v43, v43, v93
	v_fmac_f32_e32 v66, v82, v88
	v_add_f32_e32 v67, v67, v96
	v_fmac_f32_e32 v2, v10, v15
	v_lshlrev_b32_e32 v10, 16, v3
	v_lshlrev_b32_e32 v89, 16, v69
	v_lshlrev_b32_e32 v94, 16, v73
	v_lshlrev_b32_e32 v97, 16, v81
	v_add_f32_e32 v43, v43, v72
	v_fmac_f32_e32 v66, v83, v68
	v_add_f32_e32 v67, v67, v80
	v_fmac_f32_e32 v2, v12, v10
	v_and_b32_e32 v3, 0xffff0000, v3
	v_and_b32_e32 v69, 0xffff0000, v69
	v_and_b32_e32 v73, 0xffff0000, v73
	v_and_b32_e32 v81, 0xffff0000, v81
	v_add_f32_e32 v43, v43, v94
	v_fmac_f32_e32 v66, v84, v89
	v_add_f32_e32 v67, v67, v97
	v_fmac_f32_e32 v2, v13, v3
	v_lshlrev_b32_e32 v3, 16, v4
	v_add_f32_e32 v43, v43, v73
	v_fmac_f32_e32 v66, v85, v69
	v_add_f32_e32 v67, v67, v81
	v_fmac_f32_e32 v2, v6, v3
	v_and_b32_e32 v3, 0xffff0000, v4
	v_add_f32_e32 v43, 0, v43
	v_add_f32_e32 v66, 0, v66
	v_cndmask_b32_e64 v67, 0, v67, s[0:1]
	v_cmp_lt_u32_e64 s[0:1], v56, v53
	v_fmac_f32_e32 v2, v7, v3
	v_lshlrev_b32_e32 v3, 16, v5
	v_cndmask_b32_e64 v43, 0, v43, s[0:1]
	v_add_f32_e32 v26, v66, v26
	v_cmp_lt_u32_e64 s[0:1], v63, v53
	v_fmac_f32_e32 v2, v8, v3
	v_and_b32_e32 v3, 0xffff0000, v5
	v_add_f32_e32 v43, v43, v67
	v_cndmask_b32_e64 v27, 0, v27, s[0:1]
	v_add_f32_e32 v18, v26, v18
	v_cmp_lt_u32_e64 s[0:1], v64, v53
	v_fmac_f32_e32 v2, v9, v3
	v_add_f32_e32 v27, v43, v27
	v_cndmask_b32_e64 v14, 0, v14, s[0:1]
	v_add_f32_e32 v2, v18, v2
	v_add_f32_e32 v14, v27, v14
	v_cndmask_b32_e64 v2, v2, 0, vcc
	ds_bpermute_b32 v3, v0, v14
	ds_bpermute_b32 v4, v0, v2
	s_movk_i32 s0, 0x7ff
	v_ashrrev_i32_e32 v53, 31, v52
	v_cmp_lt_u32_e32 vcc, s0, v65
	s_waitcnt lgkmcnt(1)
	v_add_f32_e32 v3, v14, v3
	s_waitcnt lgkmcnt(0)
	v_add_f32_e32 v2, v2, v4
	ds_bpermute_b32 v5, v57, v3
	ds_bpermute_b32 v4, v57, v2
	s_waitcnt lgkmcnt(1)
	v_add_f32_e32 v3, v3, v5
	s_waitcnt lgkmcnt(0)
	v_add_f32_e32 v2, v2, v4
	ds_bpermute_b32 v5, v58, v3
	ds_bpermute_b32 v4, v58, v2
	s_waitcnt lgkmcnt(1)
	v_add_f32_e32 v3, v3, v5
	s_waitcnt lgkmcnt(0)
	v_add_f32_e32 v2, v2, v4
	ds_bpermute_b32 v5, v59, v3
	ds_bpermute_b32 v4, v59, v2
	s_waitcnt lgkmcnt(1)
	v_add_f32_e32 v3, v3, v5
	s_waitcnt lgkmcnt(0)
	v_add_f32_e32 v4, v2, v4
	ds_bpermute_b32 v5, v60, v3
	ds_bpermute_b32 v6, v60, v4
	s_waitcnt lgkmcnt(1)
	v_add_f32_e32 v2, v3, v5
	s_waitcnt lgkmcnt(0)
	v_add_f32_e32 v5, v4, v6
	ds_bpermute_b32 v3, v61, v2
	ds_bpermute_b32 v6, v61, v5
	s_and_saveexec_b64 s[0:1], s[4:5]
	s_cbranch_execz .LBB0_479
	v_lshl_add_u32 v7, v54, 15, s20
	s_waitcnt lgkmcnt(1)
	v_add_f32_e32 v4, v2, v3
	v_or_b32_e32 v2, v7, v65
	v_ashrrev_i32_e32 v3, 31, v2
	s_and_saveexec_b64 s[12:13], vcc
	s_xor_b64 s[12:13], exec, s[12:13]
	s_cbranch_execz .LBB0_478
	s_waitcnt lgkmcnt(0)
	v_add_f32_e32 v5, v5, v6
	v_or_b32_e32 v6, v7, v55
	v_ashrrev_i32_e32 v7, 31, v6
	v_lshl_add_u64 v[6:7], v[6:7], 2, s[6:7]
	v_add_co_u32_e32 v6, vcc, -4, v6
	s_nop 1
	v_addc_co_u32_e32 v7, vcc, -1, v7, vcc
	v_mov_b32_e32 v8, v102
	v_lshl_add_u64 v[6:7], v[2:3], 2, s[6:7]
	v_mov_b32_e32 v6, v103
	s_waitcnt vmcnt(0) lgkmcnt(0)
	v_sub_f32_e32 v6, v8, v6
	v_mul_f32_e32 v6, 0x3fb8aa3b, v6
	v_exp_f32_e32 v6, v6
	s_nop 0
	v_fmac_f32_e32 v4, v5, v6
	s_branch .LBB0_478
